# v72 + local seams issue the L1 invalidate at arrival (overlaps the wait) instead of after it
# speedup vs baseline: 1.0512x; 1.0060x over previous
; __device__ __forceinline__ unsigned xb_ld(unsigned* p)              { return __hip_atomic_load(p, __ATOMIC_RELAXED, __HIP_MEMORY_SCOPE_AGENT); }
; __device__ __forceinline__ unsigned xb_add(unsigned* p, unsigned v) { return __hip_atomic_fetch_add(p, v, __ATOMIC_RELAXED, __HIP_MEMORY_SCOPE_AGENT); }
; #define XB_SPIN(cond, bar) do { unsigned _sp = 0; while (cond) { __builtin_amdgcn_s_sleep(1); \
;     if ((++_sp & 255u) == 0u) { if (xb_ld(&(bar)[XB_TMO])) break; if (_sp > XB_SPIN_CAP) { atomicAdd(&(bar)[XB_TMO], 1u); break; } } } } while (0)
; #define SEAM(k) do { if (IN(k) && IN((k) + 1)) { xcd_barrier(bar, wave == 0 && mk_lane() == 0); } } while (0)
; __device__ __forceinline__ void xcd_barrier(const XcdBarrier& b, bool leader) {
;     asm volatile("s_waitcnt vmcnt(0)" ::: "memory");
;     __syncthreads();
;     if (leader) {
;         unsigned* bar = b.bar;
;         __builtin_amdgcn_s_waitcnt(0);
;         unsigned nloc = b.st[0], nx = b.st[1];
;         if (nloc == 0u) { xcd_barrier_complete(bar, b.x, nloc, nx); b.st[0] = nloc; b.st[1] = nx; }
;         const unsigned old = xb_add(&bar[XB_XSUB(b.x)], 1u);
;         const unsigned gen = old / nloc;
;         if (old + 1u == (gen + 1u) * nloc) {
;             __builtin_amdgcn_fence(__ATOMIC_RELEASE, "agent");
;             asm volatile("s_waitcnt vmcnt(0)" ::: "memory");
;             const unsigned og = xb_add(&bar[XB_TOP], 1u);
;             const unsigned tg = og / nx;
;             if (og + 1u == (tg + 1u) * nx) xb_add(&bar[XB_TOPGEN], 1u);
;             else XB_SPIN(xb_ld(&bar[XB_TOPGEN]) == tg, bar);
;             __builtin_amdgcn_fence(__ATOMIC_ACQUIRE, "agent");
;             xb_add(&bar[XB_XGEN(b.x)], 1u);
;             asm volatile("s_waitcnt vmcnt(0)" ::: "memory");
;         } else {
;             XB_SPIN(xb_ld(&bar[XB_XGEN(b.x)]) == gen, bar);
;             __builtin_amdgcn_fence(__ATOMIC_ACQUIRE, "agent");
;             asm volatile("s_waitcnt vmcnt(0)" ::: "memory");
;         }
;     }
;     __syncthreads();
; }
; __global__ void __launch_bounds__(NWAVES * 64, 2) mk_fwd(Params P) {
;     ...
;           pg8::gemm_phase<pg8::EpiProj, pg8::StaticOrder, true, true>(lds, g, S, E, wave); }
;     }
;     SEAM(1);
.LBB0_463:
	s_waitcnt vmcnt(0)
	s_waitcnt lgkmcnt(0)
	s_barrier
	s_and_saveexec_b64 s[4:5], s[6:7]
	s_cbranch_execz .LBB0_511
	v_readlane_b32 s8, v254, 2
	v_readlane_b32 s9, v254, 3
	s_and_b32 s2, s88, 7
	s_lshl_b32 s2, s2, 8
	s_add_u32 s2, s8, s2
	s_addc_u32 s3, s9, 0
	v_mov_b32_e32 v0, 0
	v_mov_b32_e32 v1, 1
	v_mov_b32_e32 v5, 0x1400
	global_load_dwordx4 v[6:9], v0, s[8:9] offset:768 sc1
	global_load_dwordx4 v[10:13], v0, s[8:9] offset:784 sc1
	global_atomic_add v3, v5, v1, s[2:3] offset:128 sc0
	buffer_inv sc1
	s_waitcnt vmcnt(0)
	v_add_u32_e32 v14, -1, v6
	v_and_b32_e32 v2, v14, v6
	v_add_u32_e32 v14, -1, v7
	v_and_or_b32 v2, v14, v7, v2
	v_add_u32_e32 v14, -1, v8
	v_and_or_b32 v2, v14, v8, v2
	v_add_u32_e32 v14, -1, v9
	v_and_or_b32 v2, v14, v9, v2
	v_add_u32_e32 v14, -1, v10
	v_and_or_b32 v2, v14, v10, v2
	v_add_u32_e32 v14, -1, v11
	v_and_or_b32 v2, v14, v11, v2
	v_add_u32_e32 v14, -1, v12
	v_and_or_b32 v2, v14, v12, v2
	v_add_u32_e32 v14, -1, v13
	v_and_or_b32 v2, v14, v13, v2
	v_cmp_ne_u32_e32 vcc, 0, v2
	s_cbranch_vccnz .Lmy_glob_k1
	v_and_b32_e32 v4, 0xffffffe0, v3
	v_add_u32_e32 v4, 32, v4
	v_add_u32_e32 v3, 1, v3
	v_cmp_eq_u32_e32 vcc, v3, v4
	s_cbranch_vccnz .Lmy_done_k1
	s_mov_b32 s10, 0

; __device__ __forceinline__ unsigned xb_ld(unsigned* p)              { return __hip_atomic_load(p, __ATOMIC_RELAXED, __HIP_MEMORY_SCOPE_AGENT); }
; #define XB_SPIN(cond, bar) do { unsigned _sp = 0; while (cond) { __builtin_amdgcn_s_sleep(1); \
;     if ((++_sp & 255u) == 0u) { if (xb_ld(&(bar)[XB_TMO])) break; if (_sp > XB_SPIN_CAP) { atomicAdd(&(bar)[XB_TMO], 1u); break; } } } } while (0)
; __device__ __forceinline__ void xcd_barrier(const XcdBarrier& b, bool leader) {
;     ...
;             XB_SPIN(xb_ld(&bar[XB_XGEN(b.x)]) == gen, bar);
;             __builtin_amdgcn_fence(__ATOMIC_ACQUIRE, "agent");
;             asm volatile("s_waitcnt vmcnt(0)" ::: "memory");
;         }
;     }
;     __syncthreads();
.Lmy_done_k1:
	s_waitcnt vmcnt(0)
	s_branch .LBB0_511

; __device__ __forceinline__ unsigned xb_ld(unsigned* p)              { return __hip_atomic_load(p, __ATOMIC_RELAXED, __HIP_MEMORY_SCOPE_AGENT); }
; __device__ __forceinline__ unsigned xb_add(unsigned* p, unsigned v) { return __hip_atomic_fetch_add(p, v, __ATOMIC_RELAXED, __HIP_MEMORY_SCOPE_AGENT); }
; #define XB_SPIN(cond, bar) do { unsigned _sp = 0; while (cond) { __builtin_amdgcn_s_sleep(1); \
;     if ((++_sp & 255u) == 0u) { if (xb_ld(&(bar)[XB_TMO])) break; if (_sp > XB_SPIN_CAP) { atomicAdd(&(bar)[XB_TMO], 1u); break; } } } } while (0)
; #define SEAM(k) do { if (IN(k) && IN((k) + 1)) { xcd_barrier(bar, wave == 0 && mk_lane() == 0); } } while (0)
; __device__ __forceinline__ void xcd_barrier(const XcdBarrier& b, bool leader) {
;     asm volatile("s_waitcnt vmcnt(0)" ::: "memory");
;     __syncthreads();
;     if (leader) {
;         unsigned* bar = b.bar;
;         __builtin_amdgcn_s_waitcnt(0);
;         unsigned nloc = b.st[0], nx = b.st[1];
;         if (nloc == 0u) { xcd_barrier_complete(bar, b.x, nloc, nx); b.st[0] = nloc; b.st[1] = nx; }
;         const unsigned old = xb_add(&bar[XB_XSUB(b.x)], 1u);
;         const unsigned gen = old / nloc;
;         if (old + 1u == (gen + 1u) * nloc) {
;             __builtin_amdgcn_fence(__ATOMIC_RELEASE, "agent");
;             asm volatile("s_waitcnt vmcnt(0)" ::: "memory");
;             const unsigned og = xb_add(&bar[XB_TOP], 1u);
;             const unsigned tg = og / nx;
;             if (og + 1u == (tg + 1u) * nx) xb_add(&bar[XB_TOPGEN], 1u);
;             else XB_SPIN(xb_ld(&bar[XB_TOPGEN]) == tg, bar);
;             __builtin_amdgcn_fence(__ATOMIC_ACQUIRE, "agent");
;             xb_add(&bar[XB_XGEN(b.x)], 1u);
;             asm volatile("s_waitcnt vmcnt(0)" ::: "memory");
;         } else {
;             XB_SPIN(xb_ld(&bar[XB_XGEN(b.x)]) == gen, bar);
;             __builtin_amdgcn_fence(__ATOMIC_ACQUIRE, "agent");
;             asm volatile("s_waitcnt vmcnt(0)" ::: "memory");
;         }
;     }
;     __syncthreads();
; }
; __global__ void __launch_bounds__(NWAVES * 64, 2) mk_fwd(Params P) {
;     ...
;         pg8::EpiRes2<true, true> E{XN, H1B, SS1};
;         pg8::gemm_phase<pg8::EpiRes2<true, true>, pg8::StaticOrder, true, true>(lds, g, S, E, wave); }
;     SEAM(4);
.LBB0_942:
	s_waitcnt vmcnt(0)
	s_waitcnt lgkmcnt(0)
	s_barrier
	s_and_saveexec_b64 s[0:1], s[6:7]
	s_cbranch_execz .LBB0_990
	v_readlane_b32 s8, v254, 2
	v_readlane_b32 s9, v254, 3
	s_and_b32 s2, s88, 7
	s_lshl_b32 s2, s2, 8
	s_add_u32 s2, s8, s2
	s_addc_u32 s3, s9, 0
	v_mov_b32_e32 v0, 0
	v_mov_b32_e32 v1, 1
	v_mov_b32_e32 v5, 0x1400
	global_load_dwordx4 v[6:9], v0, s[8:9] offset:768 sc1
	global_load_dwordx4 v[10:13], v0, s[8:9] offset:784 sc1
	global_atomic_add v3, v5, v1, s[2:3] offset:128 sc0
	buffer_inv sc1
	s_waitcnt vmcnt(0)
	v_add_u32_e32 v14, -1, v6
	v_and_b32_e32 v2, v14, v6
	v_add_u32_e32 v14, -1, v7
	v_and_or_b32 v2, v14, v7, v2
	v_add_u32_e32 v14, -1, v8
	v_and_or_b32 v2, v14, v8, v2
	v_add_u32_e32 v14, -1, v9
	v_and_or_b32 v2, v14, v9, v2
	v_add_u32_e32 v14, -1, v10
	v_and_or_b32 v2, v14, v10, v2
	v_add_u32_e32 v14, -1, v11
	v_and_or_b32 v2, v14, v11, v2
	v_add_u32_e32 v14, -1, v12
	v_and_or_b32 v2, v14, v12, v2
	v_add_u32_e32 v14, -1, v13
	v_and_or_b32 v2, v14, v13, v2
	v_cmp_ne_u32_e32 vcc, 0, v2
	s_cbranch_vccnz .Lmy_glob_k4
	v_and_b32_e32 v4, 0xffffffe0, v3
	v_add_u32_e32 v4, 32, v4
	v_add_u32_e32 v3, 1, v3
	v_cmp_eq_u32_e32 vcc, v3, v4
	s_cbranch_vccnz .Lmy_done_k4
	s_mov_b32 s10, 0

; #define LAS __attribute__((address_space(3)))
; __device__ __forceinline__ unsigned xb_ld(unsigned* p)              { return __hip_atomic_load(p, __ATOMIC_RELAXED, __HIP_MEMORY_SCOPE_AGENT); }
; __device__ __forceinline__ unsigned xb_add(unsigned* p, unsigned v) { return __hip_atomic_fetch_add(p, v, __ATOMIC_RELAXED, __HIP_MEMORY_SCOPE_AGENT); }
; #define XB_SPIN(cond, bar) do { unsigned _sp = 0; while (cond) { __builtin_amdgcn_s_sleep(1); \
;     if ((++_sp & 255u) == 0u) { if (xb_ld(&(bar)[XB_TMO])) break; if (_sp > XB_SPIN_CAP) { atomicAdd(&(bar)[XB_TMO], 1u); break; } } } } while (0)
; __device__ __forceinline__ void xcd_barrier(const XcdBarrier& b, bool leader) {
;     asm volatile("s_waitcnt vmcnt(0)" ::: "memory");
;     __syncthreads();
;     if (leader) {
;         unsigned* bar = b.bar;
;         __builtin_amdgcn_s_waitcnt(0);
;         unsigned nloc = b.st[0], nx = b.st[1];
;         if (nloc == 0u) { xcd_barrier_complete(bar, b.x, nloc, nx); b.st[0] = nloc; b.st[1] = nx; }
;         const unsigned old = xb_add(&bar[XB_XSUB(b.x)], 1u);
;         const unsigned gen = old / nloc;
;         if (old + 1u == (gen + 1u) * nloc) {
;             __builtin_amdgcn_fence(__ATOMIC_RELEASE, "agent");
;             asm volatile("s_waitcnt vmcnt(0)" ::: "memory");
;             const unsigned og = xb_add(&bar[XB_TOP], 1u);
;             const unsigned tg = og / nx;
;             if (og + 1u == (tg + 1u) * nx) xb_add(&bar[XB_TOPGEN], 1u);
;             else XB_SPIN(xb_ld(&bar[XB_TOPGEN]) == tg, bar);
;             __builtin_amdgcn_fence(__ATOMIC_ACQUIRE, "agent");
;             xb_add(&bar[XB_XGEN(b.x)], 1u);
;             asm volatile("s_waitcnt vmcnt(0)" ::: "memory");
;         } else {
;             XB_SPIN(xb_ld(&bar[XB_XGEN(b.x)]) == gen, bar);
;             __builtin_amdgcn_fence(__ATOMIC_ACQUIRE, "agent");
;             asm volatile("s_waitcnt vmcnt(0)" ::: "memory");
;         }
;     }
;     __syncthreads();
; }
; __global__ void __launch_bounds__(NWAVES * 64, 2) mk_fwd(Params P) {
;     ...
;         pg8::EpiRowScale<0> E{CQ, D, SS1, EPS, pg8::CROSS_C2, (const LAS int*)(lds + RING_BYTES + 1536), (const LAS float*)(lds + RING_BYTES + 2048)};
;         pg8::gemm_phase<pg8::EpiRowScale<0>, pg8::StaticOrder, true, true>(lds, g, S, E, wave); }
;     SEAM(5);
.LBB0_1092:
	s_waitcnt vmcnt(0)
	s_waitcnt vmcnt(0) lgkmcnt(0)
	s_barrier
	s_and_saveexec_b64 s[4:5], s[6:7]
	s_cbranch_execz .LBB0_1140
	v_readlane_b32 s8, v254, 2
	v_readlane_b32 s9, v254, 3
	s_and_b32 s2, s88, 7
	s_lshl_b32 s2, s2, 8
	s_add_u32 s2, s8, s2
	s_addc_u32 s3, s9, 0
	v_mov_b32_e32 v0, 0
	v_mov_b32_e32 v1, 1
	v_mov_b32_e32 v5, 0x1400
	global_load_dwordx4 v[6:9], v0, s[8:9] offset:768 sc1
	global_load_dwordx4 v[10:13], v0, s[8:9] offset:784 sc1
	global_atomic_add v3, v5, v1, s[2:3] offset:128 sc0
	buffer_inv sc1
	s_waitcnt vmcnt(0)
	v_add_u32_e32 v14, -1, v6
	v_and_b32_e32 v2, v14, v6
	v_add_u32_e32 v14, -1, v7
	v_and_or_b32 v2, v14, v7, v2
	v_add_u32_e32 v14, -1, v8
	v_and_or_b32 v2, v14, v8, v2
	v_add_u32_e32 v14, -1, v9
	v_and_or_b32 v2, v14, v9, v2
	v_add_u32_e32 v14, -1, v10
	v_and_or_b32 v2, v14, v10, v2
	v_add_u32_e32 v14, -1, v11
	v_and_or_b32 v2, v14, v11, v2
	v_add_u32_e32 v14, -1, v12
	v_and_or_b32 v2, v14, v12, v2
	v_add_u32_e32 v14, -1, v13
	v_and_or_b32 v2, v14, v13, v2
	v_cmp_ne_u32_e32 vcc, 0, v2
	s_cbranch_vccnz .Lmy_glob_k5
	v_and_b32_e32 v4, 0xffffffe0, v3
	v_add_u32_e32 v4, 32, v4
	v_add_u32_e32 v3, 1, v3
	v_cmp_eq_u32_e32 vcc, v3, v4
	s_cbranch_vccnz .Lmy_done_k5
	s_mov_b32 s10, 0

; __device__ __forceinline__ unsigned xb_ld(unsigned* p)              { return __hip_atomic_load(p, __ATOMIC_RELAXED, __HIP_MEMORY_SCOPE_AGENT); }
; __device__ __forceinline__ unsigned xb_add(unsigned* p, unsigned v) { return __hip_atomic_fetch_add(p, v, __ATOMIC_RELAXED, __HIP_MEMORY_SCOPE_AGENT); }
; #define XB_SPIN(cond, bar) do { unsigned _sp = 0; while (cond) { __builtin_amdgcn_s_sleep(1); \
;     if ((++_sp & 255u) == 0u) { if (xb_ld(&(bar)[XB_TMO])) break; if (_sp > XB_SPIN_CAP) { atomicAdd(&(bar)[XB_TMO], 1u); break; } } } } while (0)
; #define SEAM(k) do { if (IN(k) && IN((k) + 1)) { xcd_barrier(bar, wave == 0 && mk_lane() == 0); } } while (0)
; __device__ __forceinline__ void xcd_barrier(const XcdBarrier& b, bool leader) {
;     asm volatile("s_waitcnt vmcnt(0)" ::: "memory");
;     __syncthreads();
;     if (leader) {
;         unsigned* bar = b.bar;
;         __builtin_amdgcn_s_waitcnt(0);
;         unsigned nloc = b.st[0], nx = b.st[1];
;         if (nloc == 0u) { xcd_barrier_complete(bar, b.x, nloc, nx); b.st[0] = nloc; b.st[1] = nx; }
;         const unsigned old = xb_add(&bar[XB_XSUB(b.x)], 1u);
;         const unsigned gen = old / nloc;
;         if (old + 1u == (gen + 1u) * nloc) {
;             __builtin_amdgcn_fence(__ATOMIC_RELEASE, "agent");
;             asm volatile("s_waitcnt vmcnt(0)" ::: "memory");
;             const unsigned og = xb_add(&bar[XB_TOP], 1u);
;             const unsigned tg = og / nx;
;             if (og + 1u == (tg + 1u) * nx) xb_add(&bar[XB_TOPGEN], 1u);
;             else XB_SPIN(xb_ld(&bar[XB_TOPGEN]) == tg, bar);
;             __builtin_amdgcn_fence(__ATOMIC_ACQUIRE, "agent");
;             xb_add(&bar[XB_XGEN(b.x)], 1u);
;             asm volatile("s_waitcnt vmcnt(0)" ::: "memory");
;         } else {
;             XB_SPIN(xb_ld(&bar[XB_XGEN(b.x)]) == gen, bar);
;             __builtin_amdgcn_fence(__ATOMIC_ACQUIRE, "agent");
;             asm volatile("s_waitcnt vmcnt(0)" ::: "memory");
;         }
;     }
;     __syncthreads();
; }
; __global__ void __launch_bounds__(NWAVES * 64, 2) mk_fwd(Params P) {
;     ...
;         for (int u = vcu * upc; u < (vcu + 1) * upc && u < 512; ++u) { const int bh = u >> 4, qblk = u & 15; xattn::unit(bh >> 2, bh & 3, qblk, CQ, CKb, CVT, CO, lds, wave); }
;     }
;     SEAM(6);
.LBB0_1150:
	s_waitcnt vmcnt(0)
	s_waitcnt vmcnt(0) lgkmcnt(0)
	s_barrier
	s_and_saveexec_b64 s[0:1], s[6:7]
	s_cbranch_execz .LBB0_1198
	v_readlane_b32 s8, v254, 2
	v_readlane_b32 s9, v254, 3
	s_and_b32 s2, s88, 7
	s_lshl_b32 s2, s2, 8
	s_add_u32 s2, s8, s2
	s_addc_u32 s3, s9, 0
	v_mov_b32_e32 v0, 0
	v_mov_b32_e32 v1, 1
	v_mov_b32_e32 v5, 0x1400
	global_load_dwordx4 v[6:9], v0, s[8:9] offset:768 sc1
	global_load_dwordx4 v[10:13], v0, s[8:9] offset:784 sc1
	global_atomic_add v3, v5, v1, s[2:3] offset:128 sc0
	buffer_inv sc1
	s_waitcnt vmcnt(0)
	v_add_u32_e32 v14, -1, v6
	v_and_b32_e32 v2, v14, v6
	v_add_u32_e32 v14, -1, v7
	v_and_or_b32 v2, v14, v7, v2
	v_add_u32_e32 v14, -1, v8
	v_and_or_b32 v2, v14, v8, v2
	v_add_u32_e32 v14, -1, v9
	v_and_or_b32 v2, v14, v9, v2
	v_add_u32_e32 v14, -1, v10
	v_and_or_b32 v2, v14, v10, v2
	v_add_u32_e32 v14, -1, v11
	v_and_or_b32 v2, v14, v11, v2
	v_add_u32_e32 v14, -1, v12
	v_and_or_b32 v2, v14, v12, v2
	v_add_u32_e32 v14, -1, v13
	v_and_or_b32 v2, v14, v13, v2
	v_cmp_ne_u32_e32 vcc, 0, v2
	s_cbranch_vccnz .Lmy_glob_k6
	v_and_b32_e32 v4, 0xffffffe0, v3
	v_add_u32_e32 v4, 32, v4
	v_add_u32_e32 v3, 1, v3
	v_cmp_eq_u32_e32 vcc, v3, v4
	s_cbranch_vccnz .Lmy_done_k6
	s_mov_b32 s10, 0
